# FFN-up: the leading half runs the first two epilogue rows before its alignment barrier instead of idling (barrier count unchanged)
# baseline (speedup 1.0000x reference)
; #define PG8_BAR __builtin_amdgcn_s_barrier()
; #define LAS __attribute__((address_space(3)))
; __device__ __forceinline__ unsigned cvt_pk2(float lo, float hi) { f32x2c v = {lo, hi}; bf16x2c q = __builtin_convertvector(v, bf16x2c); return __builtin_bit_cast(unsigned, q); }
; template <class Epi, class Sched, bool ALIGN_EPI = false, bool SP2 = false>
; __device__ __forceinline__ void gemm_phase(PG8_LAS unsigned char* lds, const Gemm g, const Sched& S, const Epi& E) {
;     ...
;         if constexpr (ALIGN_EPI) { if (wr == 0) PG8_BAR; }
;     __device__ __forceinline__ void operator()(const f32x4 (&acc)[2][2][4][2], const pg8::Unit& u, int wr, int wc, int fr, int fq) const {
;         const int row0 = u.pm * 256 + wr * 64 + fr, col0 = u.pn * 128 + wc * 32 + 8 * fq;
;         const LAS float* rt = rt_.of(u.pm) + wr * 64 + fr;
; #pragma unroll
;         for (int ai = 0; ai < 2; ++ai)
; #pragma unroll
;             for (int m = 0; m < 4; ++m) { bf16_t* rowp = O + (size_t)(row0 + ai * 128 + m * 16) * FF + col0; const float r = rt[ai * 128 + m * 16];
;                 const float rl = -r * LOG2E, r2 = r * r; unsigned w[4];
; #pragma unroll
;                 for (int n = 0; n < 2; ++n)
; #pragma unroll
;                     for (int h = 0; h < 2; ++h) { const f32x2v g = {acc[ai][0][m][n][2 * h], acc[ai][0][m][n][2 * h + 1]}, uu = {acc[ai][1][m][n][2 * h], acc[ai][1][m][n][2 * h + 1]};
;                         const f32x2v t = g * rl; f32x2v d = {__builtin_amdgcn_exp2f(t.x), __builtin_amdgcn_exp2f(t.y)}; d = d + 1.0f;
;                         const f32x2v q = {__builtin_amdgcn_rcpf(d.x), __builtin_amdgcn_rcpf(d.y)}; const f32x2v o = ((g * uu) * r2) * q;
;                         w[2 * n + h] = cvt_pk2(o.x, o.y); }
;                 u32x4 wv; wv.x = w[0]; wv.y = w[1]; wv.z = w[2]; wv.w = w[3];
;                 *(u32x4*)rowp = wv; }
.LBB0_227:
	s_cmp_eq_u32 s34, s51
	s_cselect_b32 s13, s65, 0x300
	s_cmp_lg_u32 s34, s52
	s_cselect_b32 s13, s13, 0x100
	s_cmp_lg_u32 s34, s50
	s_cselect_b32 s13, s13, 0
	v_lshl_add_u32 v154, s13, 2, v148
	ds_read2_b32 v[156:157], v154 offset1:16
	v_pk_mul_f32 v[120:121], v[124:125], v[120:121]
	v_pk_mul_f32 v[122:123], v[126:127], v[122:123]
	v_pk_mul_f32 v[112:113], v[116:117], v[112:113]
	v_pk_mul_f32 v[114:115], v[118:119], v[114:115]
	s_waitcnt lgkmcnt(0)
	v_mul_f32_e32 v160, 0xbfb8aa3b, v156
	v_pk_mul_f32 v[162:163], v[124:125], v[160:161] op_sel_hi:[1,0]
	v_pk_mul_f32 v[124:125], v[126:127], v[160:161] op_sel_hi:[1,0]
	v_exp_f32_e32 v162, v162
	v_exp_f32_e32 v124, v124
	v_exp_f32_e32 v125, v125
	v_exp_f32_e32 v163, v163
	v_mul_f32_e32 v156, v156, v156
	v_pk_mul_f32 v[126:127], v[116:117], v[160:161] op_sel_hi:[1,0]
	v_pk_add_f32 v[124:125], v[124:125], 1.0 op_sel_hi:[1,0]
	v_pk_add_f32 v[162:163], v[162:163], 1.0 op_sel_hi:[1,0]
	v_rcp_f32_e32 v124, v124
	v_rcp_f32_e32 v125, v125
	v_rcp_f32_e32 v162, v162
	v_rcp_f32_e32 v163, v163
	v_exp_f32_e32 v126, v126
	v_exp_f32_e32 v127, v127
	v_pk_mul_f32 v[122:123], v[122:123], v[156:157] op_sel_hi:[1,0]
	v_pk_mul_f32 v[120:121], v[120:121], v[156:157] op_sel_hi:[1,0]
	v_pk_mul_f32 v[122:123], v[122:123], v[124:125]
	v_pk_mul_f32 v[124:125], v[118:119], v[160:161] op_sel_hi:[1,0]
	v_pk_mul_f32 v[120:121], v[120:121], v[162:163]
	v_exp_f32_e32 v124, v124
	v_exp_f32_e32 v125, v125
	v_cvt_pk_bf16_f32 v120, v120, v121
	v_cvt_pk_bf16_f32 v121, v122, v123
	v_pk_add_f32 v[122:123], v[126:127], 1.0 op_sel_hi:[1,0]
	v_pk_add_f32 v[116:117], v[124:125], 1.0 op_sel_hi:[1,0]
	v_rcp_f32_e32 v122, v122
	v_rcp_f32_e32 v123, v123
	v_rcp_f32_e32 v116, v116
	v_rcp_f32_e32 v117, v117
	v_pk_mul_f32 v[112:113], v[112:113], v[156:157] op_sel_hi:[1,0]
	v_lshl_or_b32 v158, s67, 7, v149
	v_pk_mul_f32 v[112:113], v[112:113], v[122:123]
	v_lshl_add_u32 v153, s34, 8, v146
	v_cvt_pk_bf16_f32 v122, v112, v113
	v_pk_mul_f32 v[112:113], v[114:115], v[156:157] op_sel_hi:[1,0]
	v_ashrrev_i32_e32 v159, 31, v158
	v_mov_b64_e32 v[144:145], s[40:41]
	v_pk_mul_f32 v[112:113], v[112:113], v[116:117]
	v_mad_i64_i32 v[164:165], s[20:21], v153, s66, v[144:145]
	v_cvt_pk_bf16_f32 v123, v112, v113
	v_lshlrev_b64 v[112:113], 1, v[158:159]
	v_lshl_add_u64 v[114:115], v[164:165], 0, v[112:113]
	global_store_dwordx4 v[114:115], v[120:123], off
	v_or_b32_e32 v115, 16, v153
	v_mul_f32_e32 v114, 0xbfb8aa3b, v157
	v_pk_mul_f32 v[116:117], v[108:109], v[114:115] op_sel_hi:[1,0]
	v_pk_mul_f32 v[104:105], v[108:109], v[104:105]
	v_pk_mul_f32 v[108:109], v[110:111], v[114:115] op_sel_hi:[1,0]
	v_exp_f32_e32 v116, v116
	v_exp_f32_e32 v117, v117
	v_exp_f32_e32 v108, v108
	v_exp_f32_e32 v109, v109
	v_pk_mul_f32 v[106:107], v[110:111], v[106:107]
	v_pk_add_f32 v[116:117], v[116:117], 1.0 op_sel_hi:[1,0]
	v_pk_mul_f32 v[110:111], v[100:101], v[114:115] op_sel_hi:[1,0]
	v_pk_add_f32 v[108:109], v[108:109], 1.0 op_sel_hi:[1,0]
	v_rcp_f32_e32 v116, v116
	v_rcp_f32_e32 v117, v117
	v_rcp_f32_e32 v108, v108
	v_rcp_f32_e32 v109, v109
	v_exp_f32_e32 v110, v110
	v_exp_f32_e32 v111, v111
	v_mul_f32_e32 v120, v157, v157
	v_pk_mul_f32 v[104:105], v[104:105], v[120:121] op_sel_hi:[1,0]
	v_pk_mul_f32 v[106:107], v[106:107], v[120:121] op_sel_hi:[1,0]
	v_pk_mul_f32 v[104:105], v[104:105], v[116:117]
	v_pk_mul_f32 v[106:107], v[106:107], v[108:109]
	v_pk_mul_f32 v[108:109], v[102:103], v[114:115] op_sel_hi:[1,0]
	v_cvt_pk_bf16_f32 v104, v104, v105
	v_cvt_pk_bf16_f32 v105, v106, v107
	v_pk_add_f32 v[106:107], v[110:111], 1.0 op_sel_hi:[1,0]
	v_exp_f32_e32 v108, v108
	v_exp_f32_e32 v109, v109
	v_rcp_f32_e32 v106, v106
	v_rcp_f32_e32 v107, v107
	v_pk_mul_f32 v[96:97], v[100:101], v[96:97]
	v_pk_add_f32 v[100:101], v[108:109], 1.0 op_sel_hi:[1,0]
	v_pk_mul_f32 v[96:97], v[96:97], v[120:121] op_sel_hi:[1,0]
	v_pk_mul_f32 v[98:99], v[102:103], v[98:99]
	v_rcp_f32_e32 v100, v100
	v_rcp_f32_e32 v101, v101
	v_pk_mul_f32 v[96:97], v[96:97], v[106:107]
	v_mad_i64_i32 v[118:119], s[20:21], v115, s66, v[144:145]
	v_cvt_pk_bf16_f32 v106, v96, v97
	v_pk_mul_f32 v[96:97], v[98:99], v[120:121] op_sel_hi:[1,0]
	ds_read2_b32 v[98:99], v154 offset0:32 offset1:48
	v_pk_mul_f32 v[96:97], v[96:97], v[100:101]
	v_pk_mul_f32 v[88:89], v[92:93], v[88:89]
	v_cvt_pk_bf16_f32 v107, v96, v97
	v_lshl_add_u64 v[96:97], v[118:119], 0, v[112:113]
	global_store_dwordx4 v[96:97], v[104:107], off
	s_and_b64 vcc, exec, s[10:11]
	s_cbranch_vccz .Lalign_skip1
	s_barrier
; __device__ __forceinline__ unsigned cvt_pk2(float lo, float hi) { f32x2c v = {lo, hi}; bf16x2c q = __builtin_convertvector(v, bf16x2c); return __builtin_bit_cast(unsigned, q); }
;     __device__ __forceinline__ void operator()(const f32x4 (&acc)[2][2][4][2], const pg8::Unit& u, int wr, int wc, int fr, int fq) const {
;     ...
;             for (int m = 0; m < 4; ++m) { bf16_t* rowp = O + (size_t)(row0 + ai * 128 + m * 16) * FF + col0; const float r = rt[ai * 128 + m * 16];
;                 const float rl = -r * LOG2E, r2 = r * r; unsigned w[4];
; #pragma unroll
;                 for (int n = 0; n < 2; ++n)
; #pragma unroll
;                     for (int h = 0; h < 2; ++h) { const f32x2v g = {acc[ai][0][m][n][2 * h], acc[ai][0][m][n][2 * h + 1]}, uu = {acc[ai][1][m][n][2 * h], acc[ai][1][m][n][2 * h + 1]};
;                         const f32x2v t = g * rl; f32x2v d = {__builtin_amdgcn_exp2f(t.x), __builtin_amdgcn_exp2f(t.y)}; d = d + 1.0f;
;                         const f32x2v q = {__builtin_amdgcn_rcpf(d.x), __builtin_amdgcn_rcpf(d.y)}; const f32x2v o = ((g * uu) * r2) * q;
;                         w[2 * n + h] = cvt_pk2(o.x, o.y); }
;                 u32x4 wv; wv.x = w[0]; wv.y = w[1]; wv.z = w[2]; wv.w = w[3];
;                 *(u32x4*)rowp = wv; }
.Lalign_skip1:
	v_or_b32_e32 v97, 32, v153
	s_waitcnt lgkmcnt(0)
	v_mul_f32_e32 v96, 0xbfb8aa3b, v98
	v_pk_mul_f32 v[100:101], v[92:93], v[96:97] op_sel_hi:[1,0]
	v_pk_mul_f32 v[92:93], v[94:95], v[96:97] op_sel_hi:[1,0]
	v_exp_f32_e32 v100, v100
	v_exp_f32_e32 v92, v92
	v_exp_f32_e32 v93, v93
	v_exp_f32_e32 v101, v101
	v_mul_f32_e32 v98, v98, v98
	v_pk_mul_f32 v[90:91], v[94:95], v[90:91]
	v_pk_add_f32 v[92:93], v[92:93], 1.0 op_sel_hi:[1,0]
	v_pk_add_f32 v[100:101], v[100:101], 1.0 op_sel_hi:[1,0]
	v_rcp_f32_e32 v92, v92
	v_rcp_f32_e32 v93, v93
	v_rcp_f32_e32 v100, v100
	v_rcp_f32_e32 v101, v101
	v_pk_mul_f32 v[94:95], v[84:85], v[96:97] op_sel_hi:[1,0]
	v_pk_mul_f32 v[90:91], v[90:91], v[98:99] op_sel_hi:[1,0]
	v_exp_f32_e32 v94, v94
	v_exp_f32_e32 v95, v95
	v_pk_mul_f32 v[90:91], v[90:91], v[92:93]
	v_pk_mul_f32 v[92:93], v[86:87], v[96:97] op_sel_hi:[1,0]
	v_pk_mul_f32 v[88:89], v[88:89], v[98:99] op_sel_hi:[1,0]
	v_exp_f32_e32 v92, v92
	v_exp_f32_e32 v93, v93
	v_pk_mul_f32 v[88:89], v[88:89], v[100:101]
	v_pk_mul_f32 v[80:81], v[84:85], v[80:81]
	v_cvt_pk_bf16_f32 v88, v88, v89
	v_cvt_pk_bf16_f32 v89, v90, v91
	v_pk_add_f32 v[90:91], v[94:95], 1.0 op_sel_hi:[1,0]
	v_pk_add_f32 v[84:85], v[92:93], 1.0 op_sel_hi:[1,0]
	v_rcp_f32_e32 v90, v90
	v_rcp_f32_e32 v91, v91
	v_rcp_f32_e32 v84, v84
	v_rcp_f32_e32 v85, v85
	v_pk_mul_f32 v[80:81], v[80:81], v[98:99] op_sel_hi:[1,0]
	v_pk_mul_f32 v[82:83], v[86:87], v[82:83]
	v_pk_mul_f32 v[80:81], v[80:81], v[90:91]
	v_mad_i64_i32 v[102:103], s[20:21], v97, s66, v[144:145]
	v_cvt_pk_bf16_f32 v90, v80, v81
	v_pk_mul_f32 v[80:81], v[82:83], v[98:99] op_sel_hi:[1,0]
	v_pk_mul_f32 v[72:73], v[76:77], v[72:73]
	v_pk_mul_f32 v[80:81], v[80:81], v[84:85]
	v_pk_mul_f32 v[74:75], v[78:79], v[74:75]
	v_cvt_pk_bf16_f32 v91, v80, v81
	v_lshl_add_u64 v[80:81], v[102:103], 0, v[112:113]
	global_store_dwordx4 v[80:81], v[88:91], off
	v_or_b32_e32 v81, 48, v153
	v_mul_f32_e32 v80, 0xbfb8aa3b, v99
	v_pk_mul_f32 v[82:83], v[76:77], v[80:81] op_sel_hi:[1,0]
	v_pk_mul_f32 v[76:77], v[78:79], v[80:81] op_sel_hi:[1,0]
	v_exp_f32_e32 v82, v82
	v_exp_f32_e32 v83, v83
	v_exp_f32_e32 v76, v76
	v_exp_f32_e32 v77, v77
	v_pk_mul_f32 v[78:79], v[68:69], v[80:81] op_sel_hi:[1,0]
	v_pk_add_f32 v[82:83], v[82:83], 1.0 op_sel_hi:[1,0]
	v_exp_f32_e32 v78, v78
	v_pk_add_f32 v[76:77], v[76:77], 1.0 op_sel_hi:[1,0]
	v_rcp_f32_e32 v82, v82
	v_rcp_f32_e32 v83, v83
	v_rcp_f32_e32 v76, v76
	v_rcp_f32_e32 v77, v77
	v_exp_f32_e32 v79, v79
	v_mul_f32_e32 v86, v99, v99
	v_pk_mul_f32 v[72:73], v[72:73], v[86:87] op_sel_hi:[1,0]
	v_pk_mul_f32 v[74:75], v[74:75], v[86:87] op_sel_hi:[1,0]
	v_pk_mul_f32 v[72:73], v[72:73], v[82:83]
	v_pk_mul_f32 v[74:75], v[74:75], v[76:77]
	v_pk_mul_f32 v[76:77], v[70:71], v[80:81] op_sel_hi:[1,0]
	v_cvt_pk_bf16_f32 v72, v72, v73
	v_cvt_pk_bf16_f32 v73, v74, v75
	v_pk_add_f32 v[74:75], v[78:79], 1.0 op_sel_hi:[1,0]
	v_exp_f32_e32 v76, v76
	v_exp_f32_e32 v77, v77
	v_rcp_f32_e32 v74, v74
	v_rcp_f32_e32 v75, v75
	v_pk_mul_f32 v[64:65], v[68:69], v[64:65]
	v_pk_add_f32 v[68:69], v[76:77], 1.0 op_sel_hi:[1,0]
	v_pk_mul_f32 v[64:65], v[64:65], v[86:87] op_sel_hi:[1,0]
	v_pk_mul_f32 v[66:67], v[70:71], v[66:67]
	v_rcp_f32_e32 v68, v68
	v_rcp_f32_e32 v69, v69
	v_pk_mul_f32 v[64:65], v[64:65], v[74:75]
	v_mad_i64_i32 v[84:85], s[20:21], v81, s66, v[144:145]
	v_cvt_pk_bf16_f32 v74, v64, v65
	v_pk_mul_f32 v[64:65], v[66:67], v[86:87] op_sel_hi:[1,0]
	ds_read2_b32 v[66:67], v154 offset0:128 offset1:144
	v_pk_mul_f32 v[64:65], v[64:65], v[68:69]
	v_pk_mul_f32 v[56:57], v[60:61], v[56:57]
	v_cvt_pk_bf16_f32 v75, v64, v65
	v_lshl_add_u64 v[64:65], v[84:85], 0, v[112:113]
	global_store_dwordx4 v[64:65], v[72:75], off
	v_add_u32_e32 v65, 0x80, v153
	s_waitcnt lgkmcnt(0)
	v_mul_f32_e32 v64, 0xbfb8aa3b, v66
	v_pk_mul_f32 v[68:69], v[60:61], v[64:65] op_sel_hi:[1,0]
	v_pk_mul_f32 v[60:61], v[62:63], v[64:65] op_sel_hi:[1,0]
	v_exp_f32_e32 v68, v68
	v_exp_f32_e32 v60, v60
	v_exp_f32_e32 v61, v61
	v_exp_f32_e32 v69, v69
	v_mul_f32_e32 v66, v66, v66
	v_pk_mul_f32 v[58:59], v[62:63], v[58:59]
	v_pk_add_f32 v[60:61], v[60:61], 1.0 op_sel_hi:[1,0]
	v_pk_add_f32 v[68:69], v[68:69], 1.0 op_sel_hi:[1,0]
	v_rcp_f32_e32 v60, v60
	v_rcp_f32_e32 v61, v61
	v_rcp_f32_e32 v68, v68
	v_rcp_f32_e32 v69, v69
	v_pk_mul_f32 v[62:63], v[52:53], v[64:65] op_sel_hi:[1,0]
	v_pk_mul_f32 v[58:59], v[58:59], v[66:67] op_sel_hi:[1,0]
	v_exp_f32_e32 v62, v62
	v_exp_f32_e32 v63, v63
	v_pk_mul_f32 v[58:59], v[58:59], v[60:61]
	v_pk_mul_f32 v[60:61], v[54:55], v[64:65] op_sel_hi:[1,0]
	v_pk_mul_f32 v[56:57], v[56:57], v[66:67] op_sel_hi:[1,0]
	v_exp_f32_e32 v60, v60
	v_exp_f32_e32 v61, v61
	v_pk_mul_f32 v[56:57], v[56:57], v[68:69]
	v_pk_mul_f32 v[48:49], v[52:53], v[48:49]
	v_cvt_pk_bf16_f32 v56, v56, v57
	v_cvt_pk_bf16_f32 v57, v58, v59
	v_pk_add_f32 v[58:59], v[62:63], 1.0 op_sel_hi:[1,0]
	v_pk_add_f32 v[52:53], v[60:61], 1.0 op_sel_hi:[1,0]
	v_rcp_f32_e32 v58, v58
	v_rcp_f32_e32 v59, v59
	v_rcp_f32_e32 v52, v52
	v_rcp_f32_e32 v53, v53
	v_pk_mul_f32 v[48:49], v[48:49], v[66:67] op_sel_hi:[1,0]
	v_pk_mul_f32 v[50:51], v[54:55], v[50:51]
	v_pk_mul_f32 v[48:49], v[48:49], v[58:59]
	v_mad_i64_i32 v[70:71], s[20:21], v65, s66, v[144:145]
	v_cvt_pk_bf16_f32 v58, v48, v49
	v_pk_mul_f32 v[48:49], v[50:51], v[66:67] op_sel_hi:[1,0]
	v_pk_mul_f32 v[40:41], v[44:45], v[40:41]
	v_pk_mul_f32 v[48:49], v[48:49], v[52:53]
	v_pk_mul_f32 v[42:43], v[46:47], v[42:43]
	v_cvt_pk_bf16_f32 v59, v48, v49
	v_lshl_add_u64 v[48:49], v[70:71], 0, v[112:113]
; __device__ __forceinline__ unsigned cvt_pk2(float lo, float hi) { f32x2c v = {lo, hi}; bf16x2c q = __builtin_convertvector(v, bf16x2c); return __builtin_bit_cast(unsigned, q); }
;     __device__ __forceinline__ void operator()(const f32x4 (&acc)[2][2][4][2], const pg8::Unit& u, int wr, int wc, int fr, int fq) const {
;     ...
;             for (int m = 0; m < 4; ++m) { bf16_t* rowp = O + (size_t)(row0 + ai * 128 + m * 16) * FF + col0; const float r = rt[ai * 128 + m * 16];
;                 const float rl = -r * LOG2E, r2 = r * r; unsigned w[4];
; #pragma unroll
;                 for (int n = 0; n < 2; ++n)
; #pragma unroll
;                     for (int h = 0; h < 2; ++h) { const f32x2v g = {acc[ai][0][m][n][2 * h], acc[ai][0][m][n][2 * h + 1]}, uu = {acc[ai][1][m][n][2 * h], acc[ai][1][m][n][2 * h + 1]};
;                         const f32x2v t = g * rl; f32x2v d = {__builtin_amdgcn_exp2f(t.x), __builtin_amdgcn_exp2f(t.y)}; d = d + 1.0f;
;                         const f32x2v q = {__builtin_amdgcn_rcpf(d.x), __builtin_amdgcn_rcpf(d.y)}; const f32x2v o = ((g * uu) * r2) * q;
;                         w[2 * n + h] = cvt_pk2(o.x, o.y); }
;                 u32x4 wv; wv.x = w[0]; wv.y = w[1]; wv.z = w[2]; wv.w = w[3];
;                 *(u32x4*)rowp = wv; }
	global_store_dwordx4 v[48:49], v[56:59], off
	v_add_u32_e32 v49, 0x90, v153
	v_mul_f32_e32 v48, 0xbfb8aa3b, v67
	v_pk_mul_f32 v[50:51], v[44:45], v[48:49] op_sel_hi:[1,0]
	v_pk_mul_f32 v[44:45], v[46:47], v[48:49] op_sel_hi:[1,0]
	v_exp_f32_e32 v50, v50
	v_exp_f32_e32 v51, v51
	v_exp_f32_e32 v44, v44
	v_exp_f32_e32 v45, v45
	v_pk_mul_f32 v[46:47], v[36:37], v[48:49] op_sel_hi:[1,0]
	v_pk_add_f32 v[50:51], v[50:51], 1.0 op_sel_hi:[1,0]
	v_exp_f32_e32 v46, v46
	v_pk_add_f32 v[44:45], v[44:45], 1.0 op_sel_hi:[1,0]
	v_rcp_f32_e32 v50, v50
	v_rcp_f32_e32 v51, v51
	v_rcp_f32_e32 v44, v44
	v_rcp_f32_e32 v45, v45
	v_exp_f32_e32 v47, v47
	v_mul_f32_e32 v54, v67, v67
	v_pk_mul_f32 v[40:41], v[40:41], v[54:55] op_sel_hi:[1,0]
	v_pk_mul_f32 v[42:43], v[42:43], v[54:55] op_sel_hi:[1,0]
	v_pk_mul_f32 v[40:41], v[40:41], v[50:51]
	v_pk_mul_f32 v[42:43], v[42:43], v[44:45]
	v_pk_mul_f32 v[44:45], v[38:39], v[48:49] op_sel_hi:[1,0]
	v_cvt_pk_bf16_f32 v40, v40, v41
	v_cvt_pk_bf16_f32 v41, v42, v43
	v_pk_add_f32 v[42:43], v[46:47], 1.0 op_sel_hi:[1,0]
	v_exp_f32_e32 v44, v44
	v_exp_f32_e32 v45, v45
	v_rcp_f32_e32 v42, v42
	v_rcp_f32_e32 v43, v43
	v_pk_mul_f32 v[32:33], v[36:37], v[32:33]
	v_pk_add_f32 v[36:37], v[44:45], 1.0 op_sel_hi:[1,0]
	v_pk_mul_f32 v[32:33], v[32:33], v[54:55] op_sel_hi:[1,0]
	v_pk_mul_f32 v[34:35], v[38:39], v[34:35]
	v_rcp_f32_e32 v36, v36
	v_rcp_f32_e32 v37, v37
	v_pk_mul_f32 v[32:33], v[32:33], v[42:43]
	v_mad_i64_i32 v[52:53], s[20:21], v49, s66, v[144:145]
	v_cvt_pk_bf16_f32 v42, v32, v33
	v_pk_mul_f32 v[32:33], v[34:35], v[54:55] op_sel_hi:[1,0]
	ds_read2_b32 v[34:35], v154 offset0:160 offset1:176
	v_pk_mul_f32 v[32:33], v[32:33], v[36:37]
	v_pk_mul_f32 v[24:25], v[28:29], v[24:25]
	v_cvt_pk_bf16_f32 v43, v32, v33
	v_lshl_add_u64 v[32:33], v[52:53], 0, v[112:113]
	global_store_dwordx4 v[32:33], v[40:43], off
	v_add_u32_e32 v33, 0xa0, v153
	s_waitcnt lgkmcnt(0)
	v_mul_f32_e32 v32, 0xbfb8aa3b, v34
	v_pk_mul_f32 v[36:37], v[28:29], v[32:33] op_sel_hi:[1,0]
	v_pk_mul_f32 v[28:29], v[30:31], v[32:33] op_sel_hi:[1,0]
	v_exp_f32_e32 v36, v36
	v_exp_f32_e32 v28, v28
	v_exp_f32_e32 v29, v29
	v_exp_f32_e32 v37, v37
	v_mul_f32_e32 v34, v34, v34
	v_pk_mul_f32 v[26:27], v[30:31], v[26:27]
	v_pk_add_f32 v[28:29], v[28:29], 1.0 op_sel_hi:[1,0]
	v_pk_add_f32 v[36:37], v[36:37], 1.0 op_sel_hi:[1,0]
	v_rcp_f32_e32 v28, v28
	v_rcp_f32_e32 v29, v29
	v_rcp_f32_e32 v36, v36
	v_rcp_f32_e32 v37, v37
	v_pk_mul_f32 v[30:31], v[20:21], v[32:33] op_sel_hi:[1,0]
	v_pk_mul_f32 v[26:27], v[26:27], v[34:35] op_sel_hi:[1,0]
	v_exp_f32_e32 v30, v30
	v_exp_f32_e32 v31, v31
	v_pk_mul_f32 v[26:27], v[26:27], v[28:29]
	v_pk_mul_f32 v[28:29], v[22:23], v[32:33] op_sel_hi:[1,0]
	v_pk_mul_f32 v[24:25], v[24:25], v[34:35] op_sel_hi:[1,0]
	v_exp_f32_e32 v28, v28
	v_exp_f32_e32 v29, v29
	v_pk_mul_f32 v[24:25], v[24:25], v[36:37]
	v_pk_mul_f32 v[16:17], v[20:21], v[16:17]
	v_cvt_pk_bf16_f32 v24, v24, v25
	v_cvt_pk_bf16_f32 v25, v26, v27
	v_pk_add_f32 v[26:27], v[30:31], 1.0 op_sel_hi:[1,0]
	v_pk_add_f32 v[20:21], v[28:29], 1.0 op_sel_hi:[1,0]
	v_rcp_f32_e32 v26, v26
	v_rcp_f32_e32 v27, v27
	v_rcp_f32_e32 v20, v20
	v_rcp_f32_e32 v21, v21
	v_pk_mul_f32 v[16:17], v[16:17], v[34:35] op_sel_hi:[1,0]
	v_pk_mul_f32 v[18:19], v[22:23], v[18:19]
	v_pk_mul_f32 v[16:17], v[16:17], v[26:27]
	v_mad_i64_i32 v[38:39], s[20:21], v33, s66, v[144:145]
	v_cvt_pk_bf16_f32 v26, v16, v17
	v_pk_mul_f32 v[16:17], v[18:19], v[34:35] op_sel_hi:[1,0]
	v_pk_mul_f32 v[8:9], v[12:13], v[8:9]
	v_pk_mul_f32 v[16:17], v[16:17], v[20:21]
	v_mul_f32_e32 v22, v35, v35
	v_cvt_pk_bf16_f32 v27, v16, v17
	v_lshl_add_u64 v[16:17], v[38:39], 0, v[112:113]
	global_store_dwordx4 v[16:17], v[24:27], off
	v_add_u32_e32 v17, 0xb0, v153
	v_mul_f32_e32 v16, 0xbfb8aa3b, v35
	v_pk_mul_f32 v[18:19], v[12:13], v[16:17] op_sel_hi:[1,0]
	v_pk_mul_f32 v[12:13], v[14:15], v[16:17] op_sel_hi:[1,0]
	v_exp_f32_e32 v18, v18
	v_exp_f32_e32 v12, v12
	v_exp_f32_e32 v13, v13
	v_exp_f32_e32 v19, v19
	v_pk_mul_f32 v[10:11], v[14:15], v[10:11]
	v_pk_mul_f32 v[14:15], v[4:5], v[16:17] op_sel_hi:[1,0]
	v_pk_add_f32 v[12:13], v[12:13], 1.0 op_sel_hi:[1,0]
	v_pk_add_f32 v[18:19], v[18:19], 1.0 op_sel_hi:[1,0]
	v_rcp_f32_e32 v12, v12
	v_rcp_f32_e32 v13, v13
	v_rcp_f32_e32 v18, v18
	v_rcp_f32_e32 v19, v19
	v_exp_f32_e32 v14, v14
	v_exp_f32_e32 v15, v15
	v_pk_mul_f32 v[10:11], v[10:11], v[22:23] op_sel_hi:[1,0]
	v_pk_mul_f32 v[8:9], v[8:9], v[22:23] op_sel_hi:[1,0]
	v_pk_mul_f32 v[10:11], v[10:11], v[12:13]
	v_pk_mul_f32 v[12:13], v[6:7], v[16:17] op_sel_hi:[1,0]
	v_pk_mul_f32 v[8:9], v[8:9], v[18:19]
	v_exp_f32_e32 v12, v12
	v_exp_f32_e32 v13, v13
	v_cvt_pk_bf16_f32 v8, v8, v9
	v_cvt_pk_bf16_f32 v9, v10, v11
	v_pk_add_f32 v[10:11], v[14:15], 1.0 op_sel_hi:[1,0]
	v_pk_mul_f32 v[0:1], v[4:5], v[0:1]
	v_rcp_f32_e32 v10, v10
	v_rcp_f32_e32 v11, v11
	v_pk_add_f32 v[4:5], v[12:13], 1.0 op_sel_hi:[1,0]
	v_pk_mul_f32 v[0:1], v[0:1], v[22:23] op_sel_hi:[1,0]
	v_rcp_f32_e32 v4, v4
	v_rcp_f32_e32 v5, v5
	v_pk_mul_f32 v[2:3], v[6:7], v[2:3]
	v_pk_mul_f32 v[0:1], v[0:1], v[10:11]
	v_mad_i64_i32 v[20:21], s[20:21], v17, s66, v[144:145]
	v_cvt_pk_bf16_f32 v10, v0, v1
	v_pk_mul_f32 v[0:1], v[2:3], v[22:23] op_sel_hi:[1,0]
	s_andn2_b64 vcc, exec, s[4:5]
	v_pk_mul_f32 v[0:1], v[0:1], v[4:5]
	s_mov_b64 s[4:5], -1
	v_cvt_pk_bf16_f32 v11, v0, v1
	v_lshl_add_u64 v[0:1], v[20:21], 0, v[112:113]
	global_store_dwordx4 v[0:1], v[8:11], off
	s_cbranch_vccnz .LBB0_220
	s_andn2_b64 vcc, exec, s[0:1]
	s_cbranch_vccnz .LBB0_219
	s_barrier
	s_branch .LBB0_219

; #define PG8_BAR __builtin_amdgcn_s_barrier()
; #define LAS __attribute__((address_space(3)))
; __device__ __forceinline__ unsigned cvt_pk2(float lo, float hi) { f32x2c v = {lo, hi}; bf16x2c q = __builtin_convertvector(v, bf16x2c); return __builtin_bit_cast(unsigned, q); }
; template <class Epi, class Sched, bool ALIGN_EPI = false, bool SP2 = false>
; __device__ __forceinline__ void gemm_phase(PG8_LAS unsigned char* lds, const Gemm g, const Sched& S, const Epi& E) {
;     ...
;         if constexpr (ALIGN_EPI) { if (wr == 0) PG8_BAR; }
;     __device__ __forceinline__ void operator()(const f32x4 (&acc)[2][2][4][2], const pg8::Unit& u, int wr, int wc, int fr, int fq) const {
;         const int row0 = u.pm * 256 + wr * 64 + fr, col0 = u.pn * 128 + wc * 32 + 8 * fq;
;         const LAS float* rt = rt_.of(u.pm) + wr * 64 + fr;
; #pragma unroll
;         for (int ai = 0; ai < 2; ++ai)
; #pragma unroll
;             for (int m = 0; m < 4; ++m) { bf16_t* rowp = O + (size_t)(row0 + ai * 128 + m * 16) * FF + col0; const float r = rt[ai * 128 + m * 16];
;                 const float rl = -r * LOG2E, r2 = r * r; unsigned w[4];
; #pragma unroll
;                 for (int n = 0; n < 2; ++n)
; #pragma unroll
;                     for (int h = 0; h < 2; ++h) { const f32x2v g = {acc[ai][0][m][n][2 * h], acc[ai][0][m][n][2 * h + 1]}, uu = {acc[ai][1][m][n][2 * h], acc[ai][1][m][n][2 * h + 1]};
;                         const f32x2v t = g * rl; f32x2v d = {__builtin_amdgcn_exp2f(t.x), __builtin_amdgcn_exp2f(t.y)}; d = d + 1.0f;
;                         const f32x2v q = {__builtin_amdgcn_rcpf(d.x), __builtin_amdgcn_rcpf(d.y)}; const f32x2v o = ((g * uu) * r2) * q;
;                         w[2 * n + h] = cvt_pk2(o.x, o.y); }
;                 u32x4 wv; wv.x = w[0]; wv.y = w[1]; wv.z = w[2]; wv.w = w[3];
;                 *(u32x4*)rowp = wv; }
.LBB0_813:
	s_cmp_eq_u32 s34, s48
	s_cselect_b32 s13, s62, 0x300
	s_cmp_lg_u32 s34, s49
	s_cselect_b32 s13, s13, 0x100
	s_cmp_lg_u32 s34, s47
	s_cselect_b32 s13, s13, 0
	v_lshl_add_u32 v154, s13, 2, v148
	ds_read2_b32 v[156:157], v154 offset1:16
	v_pk_mul_f32 v[120:121], v[124:125], v[120:121]
	v_pk_mul_f32 v[122:123], v[126:127], v[122:123]
	v_pk_mul_f32 v[112:113], v[116:117], v[112:113]
	v_pk_mul_f32 v[114:115], v[118:119], v[114:115]
	s_waitcnt lgkmcnt(0)
	v_mul_f32_e32 v160, 0xbfb8aa3b, v156
	v_pk_mul_f32 v[162:163], v[124:125], v[160:161] op_sel_hi:[1,0]
	v_pk_mul_f32 v[124:125], v[126:127], v[160:161] op_sel_hi:[1,0]
	v_exp_f32_e32 v162, v162
	v_exp_f32_e32 v124, v124
	v_exp_f32_e32 v125, v125
	v_exp_f32_e32 v163, v163
	v_mul_f32_e32 v156, v156, v156
	v_pk_mul_f32 v[126:127], v[116:117], v[160:161] op_sel_hi:[1,0]
	v_pk_add_f32 v[124:125], v[124:125], 1.0 op_sel_hi:[1,0]
	v_pk_add_f32 v[162:163], v[162:163], 1.0 op_sel_hi:[1,0]
	v_rcp_f32_e32 v124, v124
	v_rcp_f32_e32 v125, v125
	v_rcp_f32_e32 v162, v162
	v_rcp_f32_e32 v163, v163
	v_exp_f32_e32 v126, v126
	v_exp_f32_e32 v127, v127
	v_pk_mul_f32 v[122:123], v[122:123], v[156:157] op_sel_hi:[1,0]
	v_pk_mul_f32 v[120:121], v[120:121], v[156:157] op_sel_hi:[1,0]
	v_pk_mul_f32 v[122:123], v[122:123], v[124:125]
	v_pk_mul_f32 v[124:125], v[118:119], v[160:161] op_sel_hi:[1,0]
	v_pk_mul_f32 v[120:121], v[120:121], v[162:163]
	v_exp_f32_e32 v124, v124
	v_exp_f32_e32 v125, v125
	v_cvt_pk_bf16_f32 v120, v120, v121
	v_cvt_pk_bf16_f32 v121, v122, v123
	v_pk_add_f32 v[122:123], v[126:127], 1.0 op_sel_hi:[1,0]
	v_pk_add_f32 v[116:117], v[124:125], 1.0 op_sel_hi:[1,0]
	v_rcp_f32_e32 v122, v122
	v_rcp_f32_e32 v123, v123
	v_rcp_f32_e32 v116, v116
	v_rcp_f32_e32 v117, v117
	v_pk_mul_f32 v[112:113], v[112:113], v[156:157] op_sel_hi:[1,0]
	v_lshl_or_b32 v158, s64, 7, v149
	v_pk_mul_f32 v[112:113], v[112:113], v[122:123]
	v_lshl_add_u32 v153, s34, 8, v146
	v_cvt_pk_bf16_f32 v122, v112, v113
	v_pk_mul_f32 v[112:113], v[114:115], v[156:157] op_sel_hi:[1,0]
	v_ashrrev_i32_e32 v159, 31, v158
	v_mov_b64_e32 v[144:145], s[40:41]
	v_pk_mul_f32 v[112:113], v[112:113], v[116:117]
	v_mad_i64_i32 v[164:165], s[20:21], v153, s63, v[144:145]
	v_cvt_pk_bf16_f32 v123, v112, v113
	v_lshlrev_b64 v[112:113], 1, v[158:159]
	v_lshl_add_u64 v[114:115], v[164:165], 0, v[112:113]
	global_store_dwordx4 v[114:115], v[120:123], off
	v_or_b32_e32 v115, 16, v153
	v_mul_f32_e32 v114, 0xbfb8aa3b, v157
	v_pk_mul_f32 v[116:117], v[108:109], v[114:115] op_sel_hi:[1,0]
	v_pk_mul_f32 v[104:105], v[108:109], v[104:105]
	v_pk_mul_f32 v[108:109], v[110:111], v[114:115] op_sel_hi:[1,0]
	v_exp_f32_e32 v116, v116
	v_exp_f32_e32 v117, v117
	v_exp_f32_e32 v108, v108
	v_exp_f32_e32 v109, v109
	v_pk_mul_f32 v[106:107], v[110:111], v[106:107]
	v_pk_add_f32 v[116:117], v[116:117], 1.0 op_sel_hi:[1,0]
	v_pk_mul_f32 v[110:111], v[100:101], v[114:115] op_sel_hi:[1,0]
	v_pk_add_f32 v[108:109], v[108:109], 1.0 op_sel_hi:[1,0]
	v_rcp_f32_e32 v116, v116
	v_rcp_f32_e32 v117, v117
	v_rcp_f32_e32 v108, v108
	v_rcp_f32_e32 v109, v109
	v_exp_f32_e32 v110, v110
	v_exp_f32_e32 v111, v111
	v_mul_f32_e32 v120, v157, v157
	v_pk_mul_f32 v[104:105], v[104:105], v[120:121] op_sel_hi:[1,0]
	v_pk_mul_f32 v[106:107], v[106:107], v[120:121] op_sel_hi:[1,0]
	v_pk_mul_f32 v[104:105], v[104:105], v[116:117]
	v_pk_mul_f32 v[106:107], v[106:107], v[108:109]
	v_pk_mul_f32 v[108:109], v[102:103], v[114:115] op_sel_hi:[1,0]
	v_cvt_pk_bf16_f32 v104, v104, v105
	v_cvt_pk_bf16_f32 v105, v106, v107
	v_pk_add_f32 v[106:107], v[110:111], 1.0 op_sel_hi:[1,0]
	v_exp_f32_e32 v108, v108
	v_exp_f32_e32 v109, v109
	v_rcp_f32_e32 v106, v106
	v_rcp_f32_e32 v107, v107
	v_pk_mul_f32 v[96:97], v[100:101], v[96:97]
	v_pk_add_f32 v[100:101], v[108:109], 1.0 op_sel_hi:[1,0]
	v_pk_mul_f32 v[96:97], v[96:97], v[120:121] op_sel_hi:[1,0]
	v_pk_mul_f32 v[98:99], v[102:103], v[98:99]
	v_rcp_f32_e32 v100, v100
	v_rcp_f32_e32 v101, v101
	v_pk_mul_f32 v[96:97], v[96:97], v[106:107]
	v_mad_i64_i32 v[118:119], s[20:21], v115, s63, v[144:145]
	v_cvt_pk_bf16_f32 v106, v96, v97
	v_pk_mul_f32 v[96:97], v[98:99], v[120:121] op_sel_hi:[1,0]
	ds_read2_b32 v[98:99], v154 offset0:32 offset1:48
	v_pk_mul_f32 v[96:97], v[96:97], v[100:101]
	v_pk_mul_f32 v[88:89], v[92:93], v[88:89]
	v_cvt_pk_bf16_f32 v107, v96, v97
	v_lshl_add_u64 v[96:97], v[118:119], 0, v[112:113]
	global_store_dwordx4 v[96:97], v[104:107], off
	s_and_b64 vcc, exec, s[10:11]
	s_cbranch_vccz .Lalign_skip2
	s_barrier
; __device__ __forceinline__ unsigned cvt_pk2(float lo, float hi) { f32x2c v = {lo, hi}; bf16x2c q = __builtin_convertvector(v, bf16x2c); return __builtin_bit_cast(unsigned, q); }
;     __device__ __forceinline__ void operator()(const f32x4 (&acc)[2][2][4][2], const pg8::Unit& u, int wr, int wc, int fr, int fq) const {
;     ...
;             for (int m = 0; m < 4; ++m) { bf16_t* rowp = O + (size_t)(row0 + ai * 128 + m * 16) * FF + col0; const float r = rt[ai * 128 + m * 16];
;                 const float rl = -r * LOG2E, r2 = r * r; unsigned w[4];
; #pragma unroll
;                 for (int n = 0; n < 2; ++n)
; #pragma unroll
;                     for (int h = 0; h < 2; ++h) { const f32x2v g = {acc[ai][0][m][n][2 * h], acc[ai][0][m][n][2 * h + 1]}, uu = {acc[ai][1][m][n][2 * h], acc[ai][1][m][n][2 * h + 1]};
;                         const f32x2v t = g * rl; f32x2v d = {__builtin_amdgcn_exp2f(t.x), __builtin_amdgcn_exp2f(t.y)}; d = d + 1.0f;
;                         const f32x2v q = {__builtin_amdgcn_rcpf(d.x), __builtin_amdgcn_rcpf(d.y)}; const f32x2v o = ((g * uu) * r2) * q;
;                         w[2 * n + h] = cvt_pk2(o.x, o.y); }
;                 u32x4 wv; wv.x = w[0]; wv.y = w[1]; wv.z = w[2]; wv.w = w[3];
;                 *(u32x4*)rowp = wv; }
.Lalign_skip2:
	v_or_b32_e32 v97, 32, v153
	s_waitcnt lgkmcnt(0)
	v_mul_f32_e32 v96, 0xbfb8aa3b, v98
	v_pk_mul_f32 v[100:101], v[92:93], v[96:97] op_sel_hi:[1,0]
	v_pk_mul_f32 v[92:93], v[94:95], v[96:97] op_sel_hi:[1,0]
	v_exp_f32_e32 v100, v100
	v_exp_f32_e32 v92, v92
	v_exp_f32_e32 v93, v93
	v_exp_f32_e32 v101, v101
	v_mul_f32_e32 v98, v98, v98
	v_pk_mul_f32 v[90:91], v[94:95], v[90:91]
	v_pk_add_f32 v[92:93], v[92:93], 1.0 op_sel_hi:[1,0]
	v_pk_add_f32 v[100:101], v[100:101], 1.0 op_sel_hi:[1,0]
	v_rcp_f32_e32 v92, v92
	v_rcp_f32_e32 v93, v93
	v_rcp_f32_e32 v100, v100
	v_rcp_f32_e32 v101, v101
	v_pk_mul_f32 v[94:95], v[84:85], v[96:97] op_sel_hi:[1,0]
	v_pk_mul_f32 v[90:91], v[90:91], v[98:99] op_sel_hi:[1,0]
	v_exp_f32_e32 v94, v94
	v_exp_f32_e32 v95, v95
	v_pk_mul_f32 v[90:91], v[90:91], v[92:93]
	v_pk_mul_f32 v[92:93], v[86:87], v[96:97] op_sel_hi:[1,0]
	v_pk_mul_f32 v[88:89], v[88:89], v[98:99] op_sel_hi:[1,0]
	v_exp_f32_e32 v92, v92
	v_exp_f32_e32 v93, v93
	v_pk_mul_f32 v[88:89], v[88:89], v[100:101]
	v_pk_mul_f32 v[80:81], v[84:85], v[80:81]
	v_cvt_pk_bf16_f32 v88, v88, v89
	v_cvt_pk_bf16_f32 v89, v90, v91
	v_pk_add_f32 v[90:91], v[94:95], 1.0 op_sel_hi:[1,0]
	v_pk_add_f32 v[84:85], v[92:93], 1.0 op_sel_hi:[1,0]
	v_rcp_f32_e32 v90, v90
	v_rcp_f32_e32 v91, v91
	v_rcp_f32_e32 v84, v84
	v_rcp_f32_e32 v85, v85
	v_pk_mul_f32 v[80:81], v[80:81], v[98:99] op_sel_hi:[1,0]
	v_pk_mul_f32 v[82:83], v[86:87], v[82:83]
	v_pk_mul_f32 v[80:81], v[80:81], v[90:91]
	v_mad_i64_i32 v[102:103], s[20:21], v97, s63, v[144:145]
	v_cvt_pk_bf16_f32 v90, v80, v81
	v_pk_mul_f32 v[80:81], v[82:83], v[98:99] op_sel_hi:[1,0]
	v_pk_mul_f32 v[72:73], v[76:77], v[72:73]
	v_pk_mul_f32 v[80:81], v[80:81], v[84:85]
	v_pk_mul_f32 v[74:75], v[78:79], v[74:75]
	v_cvt_pk_bf16_f32 v91, v80, v81
	v_lshl_add_u64 v[80:81], v[102:103], 0, v[112:113]
	global_store_dwordx4 v[80:81], v[88:91], off
	v_or_b32_e32 v81, 48, v153
	v_mul_f32_e32 v80, 0xbfb8aa3b, v99
	v_pk_mul_f32 v[82:83], v[76:77], v[80:81] op_sel_hi:[1,0]
	v_pk_mul_f32 v[76:77], v[78:79], v[80:81] op_sel_hi:[1,0]
	v_exp_f32_e32 v82, v82
	v_exp_f32_e32 v83, v83
	v_exp_f32_e32 v76, v76
	v_exp_f32_e32 v77, v77
	v_pk_mul_f32 v[78:79], v[68:69], v[80:81] op_sel_hi:[1,0]
	v_pk_add_f32 v[82:83], v[82:83], 1.0 op_sel_hi:[1,0]
	v_exp_f32_e32 v78, v78
	v_pk_add_f32 v[76:77], v[76:77], 1.0 op_sel_hi:[1,0]
	v_rcp_f32_e32 v82, v82
	v_rcp_f32_e32 v83, v83
	v_rcp_f32_e32 v76, v76
	v_rcp_f32_e32 v77, v77
	v_exp_f32_e32 v79, v79
	v_mul_f32_e32 v86, v99, v99
	v_pk_mul_f32 v[72:73], v[72:73], v[86:87] op_sel_hi:[1,0]
	v_pk_mul_f32 v[74:75], v[74:75], v[86:87] op_sel_hi:[1,0]
	v_pk_mul_f32 v[72:73], v[72:73], v[82:83]
	v_pk_mul_f32 v[74:75], v[74:75], v[76:77]
	v_pk_mul_f32 v[76:77], v[70:71], v[80:81] op_sel_hi:[1,0]
	v_cvt_pk_bf16_f32 v72, v72, v73
	v_cvt_pk_bf16_f32 v73, v74, v75
	v_pk_add_f32 v[74:75], v[78:79], 1.0 op_sel_hi:[1,0]
	v_exp_f32_e32 v76, v76
	v_exp_f32_e32 v77, v77
	v_rcp_f32_e32 v74, v74
	v_rcp_f32_e32 v75, v75
	v_pk_mul_f32 v[64:65], v[68:69], v[64:65]
	v_pk_add_f32 v[68:69], v[76:77], 1.0 op_sel_hi:[1,0]
	v_pk_mul_f32 v[64:65], v[64:65], v[86:87] op_sel_hi:[1,0]
	v_pk_mul_f32 v[66:67], v[70:71], v[66:67]
	v_rcp_f32_e32 v68, v68
	v_rcp_f32_e32 v69, v69
	v_pk_mul_f32 v[64:65], v[64:65], v[74:75]
	v_mad_i64_i32 v[84:85], s[20:21], v81, s63, v[144:145]
	v_cvt_pk_bf16_f32 v74, v64, v65
	v_pk_mul_f32 v[64:65], v[66:67], v[86:87] op_sel_hi:[1,0]
	ds_read2_b32 v[66:67], v154 offset0:128 offset1:144
	v_pk_mul_f32 v[64:65], v[64:65], v[68:69]
	v_pk_mul_f32 v[56:57], v[60:61], v[56:57]
	v_cvt_pk_bf16_f32 v75, v64, v65
	v_lshl_add_u64 v[64:65], v[84:85], 0, v[112:113]
	global_store_dwordx4 v[64:65], v[72:75], off
	v_add_u32_e32 v65, 0x80, v153
	s_waitcnt lgkmcnt(0)
	v_mul_f32_e32 v64, 0xbfb8aa3b, v66
	v_pk_mul_f32 v[68:69], v[60:61], v[64:65] op_sel_hi:[1,0]
	v_pk_mul_f32 v[60:61], v[62:63], v[64:65] op_sel_hi:[1,0]
	v_exp_f32_e32 v68, v68
	v_exp_f32_e32 v60, v60
	v_exp_f32_e32 v61, v61
	v_exp_f32_e32 v69, v69
	v_mul_f32_e32 v66, v66, v66
	v_pk_mul_f32 v[58:59], v[62:63], v[58:59]
	v_pk_add_f32 v[60:61], v[60:61], 1.0 op_sel_hi:[1,0]
	v_pk_add_f32 v[68:69], v[68:69], 1.0 op_sel_hi:[1,0]
	v_rcp_f32_e32 v60, v60
	v_rcp_f32_e32 v61, v61
	v_rcp_f32_e32 v68, v68
	v_rcp_f32_e32 v69, v69
	v_pk_mul_f32 v[62:63], v[52:53], v[64:65] op_sel_hi:[1,0]
	v_pk_mul_f32 v[58:59], v[58:59], v[66:67] op_sel_hi:[1,0]
	v_exp_f32_e32 v62, v62
	v_exp_f32_e32 v63, v63
	v_pk_mul_f32 v[58:59], v[58:59], v[60:61]
	v_pk_mul_f32 v[60:61], v[54:55], v[64:65] op_sel_hi:[1,0]
	v_pk_mul_f32 v[56:57], v[56:57], v[66:67] op_sel_hi:[1,0]
	v_exp_f32_e32 v60, v60
	v_exp_f32_e32 v61, v61
	v_pk_mul_f32 v[56:57], v[56:57], v[68:69]
	v_pk_mul_f32 v[48:49], v[52:53], v[48:49]
	v_cvt_pk_bf16_f32 v56, v56, v57
	v_cvt_pk_bf16_f32 v57, v58, v59
	v_pk_add_f32 v[58:59], v[62:63], 1.0 op_sel_hi:[1,0]
	v_pk_add_f32 v[52:53], v[60:61], 1.0 op_sel_hi:[1,0]
	v_rcp_f32_e32 v58, v58
	v_rcp_f32_e32 v59, v59
	v_rcp_f32_e32 v52, v52
	v_rcp_f32_e32 v53, v53
	v_pk_mul_f32 v[48:49], v[48:49], v[66:67] op_sel_hi:[1,0]
	v_pk_mul_f32 v[50:51], v[54:55], v[50:51]
	v_pk_mul_f32 v[48:49], v[48:49], v[58:59]
	v_mad_i64_i32 v[70:71], s[20:21], v65, s63, v[144:145]
	v_cvt_pk_bf16_f32 v58, v48, v49
	v_pk_mul_f32 v[48:49], v[50:51], v[66:67] op_sel_hi:[1,0]
	v_pk_mul_f32 v[40:41], v[44:45], v[40:41]
	v_pk_mul_f32 v[48:49], v[48:49], v[52:53]
	v_pk_mul_f32 v[42:43], v[46:47], v[42:43]
	v_cvt_pk_bf16_f32 v59, v48, v49
	v_lshl_add_u64 v[48:49], v[70:71], 0, v[112:113]
; __device__ __forceinline__ unsigned cvt_pk2(float lo, float hi) { f32x2c v = {lo, hi}; bf16x2c q = __builtin_convertvector(v, bf16x2c); return __builtin_bit_cast(unsigned, q); }
;     __device__ __forceinline__ void operator()(const f32x4 (&acc)[2][2][4][2], const pg8::Unit& u, int wr, int wc, int fr, int fq) const {
;     ...
;             for (int m = 0; m < 4; ++m) { bf16_t* rowp = O + (size_t)(row0 + ai * 128 + m * 16) * FF + col0; const float r = rt[ai * 128 + m * 16];
;                 const float rl = -r * LOG2E, r2 = r * r; unsigned w[4];
; #pragma unroll
;                 for (int n = 0; n < 2; ++n)
; #pragma unroll
;                     for (int h = 0; h < 2; ++h) { const f32x2v g = {acc[ai][0][m][n][2 * h], acc[ai][0][m][n][2 * h + 1]}, uu = {acc[ai][1][m][n][2 * h], acc[ai][1][m][n][2 * h + 1]};
;                         const f32x2v t = g * rl; f32x2v d = {__builtin_amdgcn_exp2f(t.x), __builtin_amdgcn_exp2f(t.y)}; d = d + 1.0f;
;                         const f32x2v q = {__builtin_amdgcn_rcpf(d.x), __builtin_amdgcn_rcpf(d.y)}; const f32x2v o = ((g * uu) * r2) * q;
;                         w[2 * n + h] = cvt_pk2(o.x, o.y); }
;                 u32x4 wv; wv.x = w[0]; wv.y = w[1]; wv.z = w[2]; wv.w = w[3];
;                 *(u32x4*)rowp = wv; }
	global_store_dwordx4 v[48:49], v[56:59], off
	v_add_u32_e32 v49, 0x90, v153
	v_mul_f32_e32 v48, 0xbfb8aa3b, v67
	v_pk_mul_f32 v[50:51], v[44:45], v[48:49] op_sel_hi:[1,0]
	v_pk_mul_f32 v[44:45], v[46:47], v[48:49] op_sel_hi:[1,0]
	v_exp_f32_e32 v50, v50
	v_exp_f32_e32 v51, v51
	v_exp_f32_e32 v44, v44
	v_exp_f32_e32 v45, v45
	v_pk_mul_f32 v[46:47], v[36:37], v[48:49] op_sel_hi:[1,0]
	v_pk_add_f32 v[50:51], v[50:51], 1.0 op_sel_hi:[1,0]
	v_exp_f32_e32 v46, v46
	v_pk_add_f32 v[44:45], v[44:45], 1.0 op_sel_hi:[1,0]
	v_rcp_f32_e32 v50, v50
	v_rcp_f32_e32 v51, v51
	v_rcp_f32_e32 v44, v44
	v_rcp_f32_e32 v45, v45
	v_exp_f32_e32 v47, v47
	v_mul_f32_e32 v54, v67, v67
	v_pk_mul_f32 v[40:41], v[40:41], v[54:55] op_sel_hi:[1,0]
	v_pk_mul_f32 v[42:43], v[42:43], v[54:55] op_sel_hi:[1,0]
	v_pk_mul_f32 v[40:41], v[40:41], v[50:51]
	v_pk_mul_f32 v[42:43], v[42:43], v[44:45]
	v_pk_mul_f32 v[44:45], v[38:39], v[48:49] op_sel_hi:[1,0]
	v_cvt_pk_bf16_f32 v40, v40, v41
	v_cvt_pk_bf16_f32 v41, v42, v43
	v_pk_add_f32 v[42:43], v[46:47], 1.0 op_sel_hi:[1,0]
	v_exp_f32_e32 v44, v44
	v_exp_f32_e32 v45, v45
	v_rcp_f32_e32 v42, v42
	v_rcp_f32_e32 v43, v43
	v_pk_mul_f32 v[32:33], v[36:37], v[32:33]
	v_pk_add_f32 v[36:37], v[44:45], 1.0 op_sel_hi:[1,0]
	v_pk_mul_f32 v[32:33], v[32:33], v[54:55] op_sel_hi:[1,0]
	v_pk_mul_f32 v[34:35], v[38:39], v[34:35]
	v_rcp_f32_e32 v36, v36
	v_rcp_f32_e32 v37, v37
	v_pk_mul_f32 v[32:33], v[32:33], v[42:43]
	v_mad_i64_i32 v[52:53], s[20:21], v49, s63, v[144:145]
	v_cvt_pk_bf16_f32 v42, v32, v33
	v_pk_mul_f32 v[32:33], v[34:35], v[54:55] op_sel_hi:[1,0]
	ds_read2_b32 v[34:35], v154 offset0:160 offset1:176
	v_pk_mul_f32 v[32:33], v[32:33], v[36:37]
	v_pk_mul_f32 v[24:25], v[28:29], v[24:25]
	v_cvt_pk_bf16_f32 v43, v32, v33
	v_lshl_add_u64 v[32:33], v[52:53], 0, v[112:113]
	global_store_dwordx4 v[32:33], v[40:43], off
	v_add_u32_e32 v33, 0xa0, v153
	s_waitcnt lgkmcnt(0)
	v_mul_f32_e32 v32, 0xbfb8aa3b, v34
	v_pk_mul_f32 v[36:37], v[28:29], v[32:33] op_sel_hi:[1,0]
	v_pk_mul_f32 v[28:29], v[30:31], v[32:33] op_sel_hi:[1,0]
	v_exp_f32_e32 v36, v36
	v_exp_f32_e32 v28, v28
	v_exp_f32_e32 v29, v29
	v_exp_f32_e32 v37, v37
	v_mul_f32_e32 v34, v34, v34
	v_pk_mul_f32 v[26:27], v[30:31], v[26:27]
	v_pk_add_f32 v[28:29], v[28:29], 1.0 op_sel_hi:[1,0]
	v_pk_add_f32 v[36:37], v[36:37], 1.0 op_sel_hi:[1,0]
	v_rcp_f32_e32 v28, v28
	v_rcp_f32_e32 v29, v29
	v_rcp_f32_e32 v36, v36
	v_rcp_f32_e32 v37, v37
	v_pk_mul_f32 v[30:31], v[20:21], v[32:33] op_sel_hi:[1,0]
	v_pk_mul_f32 v[26:27], v[26:27], v[34:35] op_sel_hi:[1,0]
	v_exp_f32_e32 v30, v30
	v_exp_f32_e32 v31, v31
	v_pk_mul_f32 v[26:27], v[26:27], v[28:29]
	v_pk_mul_f32 v[28:29], v[22:23], v[32:33] op_sel_hi:[1,0]
	v_pk_mul_f32 v[24:25], v[24:25], v[34:35] op_sel_hi:[1,0]
	v_exp_f32_e32 v28, v28
	v_exp_f32_e32 v29, v29
	v_pk_mul_f32 v[24:25], v[24:25], v[36:37]
	v_pk_mul_f32 v[16:17], v[20:21], v[16:17]
	v_cvt_pk_bf16_f32 v24, v24, v25
	v_cvt_pk_bf16_f32 v25, v26, v27
	v_pk_add_f32 v[26:27], v[30:31], 1.0 op_sel_hi:[1,0]
	v_pk_add_f32 v[20:21], v[28:29], 1.0 op_sel_hi:[1,0]
	v_rcp_f32_e32 v26, v26
	v_rcp_f32_e32 v27, v27
	v_rcp_f32_e32 v20, v20
	v_rcp_f32_e32 v21, v21
	v_pk_mul_f32 v[16:17], v[16:17], v[34:35] op_sel_hi:[1,0]
	v_pk_mul_f32 v[18:19], v[22:23], v[18:19]
	v_pk_mul_f32 v[16:17], v[16:17], v[26:27]
	v_mad_i64_i32 v[38:39], s[20:21], v33, s63, v[144:145]
	v_cvt_pk_bf16_f32 v26, v16, v17
	v_pk_mul_f32 v[16:17], v[18:19], v[34:35] op_sel_hi:[1,0]
	v_pk_mul_f32 v[8:9], v[12:13], v[8:9]
	v_pk_mul_f32 v[16:17], v[16:17], v[20:21]
	v_mul_f32_e32 v22, v35, v35
	v_cvt_pk_bf16_f32 v27, v16, v17
	v_lshl_add_u64 v[16:17], v[38:39], 0, v[112:113]
	global_store_dwordx4 v[16:17], v[24:27], off
	v_add_u32_e32 v17, 0xb0, v153
	v_mul_f32_e32 v16, 0xbfb8aa3b, v35
	v_pk_mul_f32 v[18:19], v[12:13], v[16:17] op_sel_hi:[1,0]
	v_pk_mul_f32 v[12:13], v[14:15], v[16:17] op_sel_hi:[1,0]
	v_exp_f32_e32 v18, v18
	v_exp_f32_e32 v12, v12
	v_exp_f32_e32 v13, v13
	v_exp_f32_e32 v19, v19
	v_pk_mul_f32 v[10:11], v[14:15], v[10:11]
	v_pk_mul_f32 v[14:15], v[4:5], v[16:17] op_sel_hi:[1,0]
	v_pk_add_f32 v[12:13], v[12:13], 1.0 op_sel_hi:[1,0]
	v_pk_add_f32 v[18:19], v[18:19], 1.0 op_sel_hi:[1,0]
	v_rcp_f32_e32 v12, v12
	v_rcp_f32_e32 v13, v13
	v_rcp_f32_e32 v18, v18
	v_rcp_f32_e32 v19, v19
	v_exp_f32_e32 v14, v14
	v_exp_f32_e32 v15, v15
	v_pk_mul_f32 v[10:11], v[10:11], v[22:23] op_sel_hi:[1,0]
	v_pk_mul_f32 v[8:9], v[8:9], v[22:23] op_sel_hi:[1,0]
	v_pk_mul_f32 v[10:11], v[10:11], v[12:13]
	v_pk_mul_f32 v[12:13], v[6:7], v[16:17] op_sel_hi:[1,0]
	v_pk_mul_f32 v[8:9], v[8:9], v[18:19]
	v_exp_f32_e32 v12, v12
	v_exp_f32_e32 v13, v13
	v_cvt_pk_bf16_f32 v8, v8, v9
	v_cvt_pk_bf16_f32 v9, v10, v11
	v_pk_add_f32 v[10:11], v[14:15], 1.0 op_sel_hi:[1,0]
	v_pk_mul_f32 v[0:1], v[4:5], v[0:1]
	v_rcp_f32_e32 v10, v10
	v_rcp_f32_e32 v11, v11
	v_pk_add_f32 v[4:5], v[12:13], 1.0 op_sel_hi:[1,0]
	v_pk_mul_f32 v[0:1], v[0:1], v[22:23] op_sel_hi:[1,0]
	v_rcp_f32_e32 v4, v4
	v_rcp_f32_e32 v5, v5
	v_pk_mul_f32 v[2:3], v[6:7], v[2:3]
	v_pk_mul_f32 v[0:1], v[0:1], v[10:11]
	v_mad_i64_i32 v[20:21], s[20:21], v17, s63, v[144:145]
	v_cvt_pk_bf16_f32 v10, v0, v1
	v_pk_mul_f32 v[0:1], v[2:3], v[22:23] op_sel_hi:[1,0]
	s_andn2_b64 vcc, exec, s[4:5]
	v_pk_mul_f32 v[0:1], v[0:1], v[4:5]
	s_mov_b64 s[4:5], -1
	v_cvt_pk_bf16_f32 v11, v0, v1
	v_lshl_add_u64 v[0:1], v[20:21], 0, v[112:113]
	global_store_dwordx4 v[0:1], v[8:11], off
	s_cbranch_vccnz .LBB0_806
	s_andn2_b64 vcc, exec, s[0:1]
	s_cbranch_vccnz .LBB0_805
	s_barrier
	s_branch .LBB0_805

; #define PG8_BAR __builtin_amdgcn_s_barrier()
; #define LAS __attribute__((address_space(3)))
; __device__ __forceinline__ unsigned cvt_pk2(float lo, float hi) { f32x2c v = {lo, hi}; bf16x2c q = __builtin_convertvector(v, bf16x2c); return __builtin_bit_cast(unsigned, q); }
; template <class Epi, class Sched, bool ALIGN_EPI = false, bool SP2 = false>
; __device__ __forceinline__ void gemm_phase(PG8_LAS unsigned char* lds, const Gemm g, const Sched& S, const Epi& E) {
;     ...
;         if constexpr (ALIGN_EPI) { if (wr == 0) PG8_BAR; }
;     __device__ __forceinline__ void operator()(const f32x4 (&acc)[2][2][4][2], const pg8::Unit& u, int wr, int wc, int fr, int fq) const {
;         const int row0 = u.pm * 256 + wr * 64 + fr, col0 = u.pn * 128 + wc * 32 + 8 * fq;
;         const LAS float* rt = rt_.of(u.pm) + wr * 64 + fr;
; #pragma unroll
;         for (int ai = 0; ai < 2; ++ai)
; #pragma unroll
;             for (int m = 0; m < 4; ++m) { bf16_t* rowp = O + (size_t)(row0 + ai * 128 + m * 16) * FF + col0; const float r = rt[ai * 128 + m * 16];
;                 const float rl = -r * LOG2E, r2 = r * r; unsigned w[4];
; #pragma unroll
;                 for (int n = 0; n < 2; ++n)
; #pragma unroll
;                     for (int h = 0; h < 2; ++h) { const f32x2v g = {acc[ai][0][m][n][2 * h], acc[ai][0][m][n][2 * h + 1]}, uu = {acc[ai][1][m][n][2 * h], acc[ai][1][m][n][2 * h + 1]};
;                         const f32x2v t = g * rl; f32x2v d = {__builtin_amdgcn_exp2f(t.x), __builtin_amdgcn_exp2f(t.y)}; d = d + 1.0f;
;                         const f32x2v q = {__builtin_amdgcn_rcpf(d.x), __builtin_amdgcn_rcpf(d.y)}; const f32x2v o = ((g * uu) * r2) * q;
;                         w[2 * n + h] = cvt_pk2(o.x, o.y); }
;                 u32x4 wv; wv.x = w[0]; wv.y = w[1]; wv.z = w[2]; wv.w = w[3];
;                 *(u32x4*)rowp = wv; }
.LBB0_1743:
	s_cmp_eq_u32 s34, s45
	s_cselect_b32 s13, s60, 0x300
	s_cmp_lg_u32 s34, s46
	s_cselect_b32 s13, s13, 0x100
	s_cmp_lg_u32 s34, s47
	s_cselect_b32 s13, s13, 0
	v_lshl_add_u32 v154, s13, 2, v148
	ds_read2_b32 v[156:157], v154 offset1:16
	v_pk_mul_f32 v[120:121], v[124:125], v[120:121]
	v_pk_mul_f32 v[122:123], v[126:127], v[122:123]
	v_pk_mul_f32 v[112:113], v[116:117], v[112:113]
	v_pk_mul_f32 v[114:115], v[118:119], v[114:115]
	s_waitcnt lgkmcnt(0)
	v_mul_f32_e32 v160, 0xbfb8aa3b, v156
	v_pk_mul_f32 v[162:163], v[124:125], v[160:161] op_sel_hi:[1,0]
	v_pk_mul_f32 v[124:125], v[126:127], v[160:161] op_sel_hi:[1,0]
	v_exp_f32_e32 v162, v162
	v_exp_f32_e32 v124, v124
	v_exp_f32_e32 v125, v125
	v_exp_f32_e32 v163, v163
	v_mul_f32_e32 v156, v156, v156
	v_pk_mul_f32 v[126:127], v[116:117], v[160:161] op_sel_hi:[1,0]
	v_pk_add_f32 v[124:125], v[124:125], 1.0 op_sel_hi:[1,0]
	v_pk_add_f32 v[162:163], v[162:163], 1.0 op_sel_hi:[1,0]
	v_rcp_f32_e32 v124, v124
	v_rcp_f32_e32 v125, v125
	v_rcp_f32_e32 v162, v162
	v_rcp_f32_e32 v163, v163
	v_exp_f32_e32 v126, v126
	v_exp_f32_e32 v127, v127
	v_pk_mul_f32 v[122:123], v[122:123], v[156:157] op_sel_hi:[1,0]
	v_pk_mul_f32 v[120:121], v[120:121], v[156:157] op_sel_hi:[1,0]
	v_pk_mul_f32 v[122:123], v[122:123], v[124:125]
	v_pk_mul_f32 v[124:125], v[118:119], v[160:161] op_sel_hi:[1,0]
	v_pk_mul_f32 v[120:121], v[120:121], v[162:163]
	v_exp_f32_e32 v124, v124
	v_exp_f32_e32 v125, v125
	v_cvt_pk_bf16_f32 v120, v120, v121
	v_cvt_pk_bf16_f32 v121, v122, v123
	v_pk_add_f32 v[122:123], v[126:127], 1.0 op_sel_hi:[1,0]
	v_pk_add_f32 v[116:117], v[124:125], 1.0 op_sel_hi:[1,0]
	v_rcp_f32_e32 v122, v122
	v_rcp_f32_e32 v123, v123
	v_rcp_f32_e32 v116, v116
	v_rcp_f32_e32 v117, v117
	v_pk_mul_f32 v[112:113], v[112:113], v[156:157] op_sel_hi:[1,0]
	v_lshl_or_b32 v158, s62, 7, v149
	v_pk_mul_f32 v[112:113], v[112:113], v[122:123]
	v_lshl_add_u32 v153, s34, 8, v146
	v_cvt_pk_bf16_f32 v122, v112, v113
	v_pk_mul_f32 v[112:113], v[114:115], v[156:157] op_sel_hi:[1,0]
	v_ashrrev_i32_e32 v159, 31, v158
	v_mov_b64_e32 v[144:145], s[40:41]
	v_pk_mul_f32 v[112:113], v[112:113], v[116:117]
	v_mad_i64_i32 v[164:165], s[20:21], v153, s61, v[144:145]
	v_cvt_pk_bf16_f32 v123, v112, v113
	v_lshlrev_b64 v[112:113], 1, v[158:159]
	v_lshl_add_u64 v[114:115], v[164:165], 0, v[112:113]
	global_store_dwordx4 v[114:115], v[120:123], off
	v_or_b32_e32 v115, 16, v153
	v_mul_f32_e32 v114, 0xbfb8aa3b, v157
	v_pk_mul_f32 v[116:117], v[108:109], v[114:115] op_sel_hi:[1,0]
	v_pk_mul_f32 v[104:105], v[108:109], v[104:105]
	v_pk_mul_f32 v[108:109], v[110:111], v[114:115] op_sel_hi:[1,0]
	v_exp_f32_e32 v116, v116
	v_exp_f32_e32 v117, v117
	v_exp_f32_e32 v108, v108
	v_exp_f32_e32 v109, v109
	v_pk_mul_f32 v[106:107], v[110:111], v[106:107]
	v_pk_add_f32 v[116:117], v[116:117], 1.0 op_sel_hi:[1,0]
	v_pk_mul_f32 v[110:111], v[100:101], v[114:115] op_sel_hi:[1,0]
	v_pk_add_f32 v[108:109], v[108:109], 1.0 op_sel_hi:[1,0]
	v_rcp_f32_e32 v116, v116
	v_rcp_f32_e32 v117, v117
	v_rcp_f32_e32 v108, v108
	v_rcp_f32_e32 v109, v109
	v_exp_f32_e32 v110, v110
	v_exp_f32_e32 v111, v111
	v_mul_f32_e32 v120, v157, v157
	v_pk_mul_f32 v[104:105], v[104:105], v[120:121] op_sel_hi:[1,0]
	v_pk_mul_f32 v[106:107], v[106:107], v[120:121] op_sel_hi:[1,0]
	v_pk_mul_f32 v[104:105], v[104:105], v[116:117]
	v_pk_mul_f32 v[106:107], v[106:107], v[108:109]
	v_pk_mul_f32 v[108:109], v[102:103], v[114:115] op_sel_hi:[1,0]
	v_cvt_pk_bf16_f32 v104, v104, v105
	v_cvt_pk_bf16_f32 v105, v106, v107
	v_pk_add_f32 v[106:107], v[110:111], 1.0 op_sel_hi:[1,0]
	v_exp_f32_e32 v108, v108
	v_exp_f32_e32 v109, v109
	v_rcp_f32_e32 v106, v106
	v_rcp_f32_e32 v107, v107
	v_pk_mul_f32 v[96:97], v[100:101], v[96:97]
	v_pk_add_f32 v[100:101], v[108:109], 1.0 op_sel_hi:[1,0]
	v_pk_mul_f32 v[96:97], v[96:97], v[120:121] op_sel_hi:[1,0]
	v_pk_mul_f32 v[98:99], v[102:103], v[98:99]
	v_rcp_f32_e32 v100, v100
	v_rcp_f32_e32 v101, v101
	v_pk_mul_f32 v[96:97], v[96:97], v[106:107]
	v_mad_i64_i32 v[118:119], s[20:21], v115, s61, v[144:145]
	v_cvt_pk_bf16_f32 v106, v96, v97
	v_pk_mul_f32 v[96:97], v[98:99], v[120:121] op_sel_hi:[1,0]
	ds_read2_b32 v[98:99], v154 offset0:32 offset1:48
	v_pk_mul_f32 v[96:97], v[96:97], v[100:101]
	v_pk_mul_f32 v[88:89], v[92:93], v[88:89]
	v_cvt_pk_bf16_f32 v107, v96, v97
	v_lshl_add_u64 v[96:97], v[118:119], 0, v[112:113]
	global_store_dwordx4 v[96:97], v[104:107], off
	s_and_b64 vcc, exec, s[10:11]
	s_cbranch_vccz .Lalign_skip4
	s_barrier
; __device__ __forceinline__ unsigned cvt_pk2(float lo, float hi) { f32x2c v = {lo, hi}; bf16x2c q = __builtin_convertvector(v, bf16x2c); return __builtin_bit_cast(unsigned, q); }
;     __device__ __forceinline__ void operator()(const f32x4 (&acc)[2][2][4][2], const pg8::Unit& u, int wr, int wc, int fr, int fq) const {
;     ...
;             for (int m = 0; m < 4; ++m) { bf16_t* rowp = O + (size_t)(row0 + ai * 128 + m * 16) * FF + col0; const float r = rt[ai * 128 + m * 16];
;                 const float rl = -r * LOG2E, r2 = r * r; unsigned w[4];
; #pragma unroll
;                 for (int n = 0; n < 2; ++n)
; #pragma unroll
;                     for (int h = 0; h < 2; ++h) { const f32x2v g = {acc[ai][0][m][n][2 * h], acc[ai][0][m][n][2 * h + 1]}, uu = {acc[ai][1][m][n][2 * h], acc[ai][1][m][n][2 * h + 1]};
;                         const f32x2v t = g * rl; f32x2v d = {__builtin_amdgcn_exp2f(t.x), __builtin_amdgcn_exp2f(t.y)}; d = d + 1.0f;
;                         const f32x2v q = {__builtin_amdgcn_rcpf(d.x), __builtin_amdgcn_rcpf(d.y)}; const f32x2v o = ((g * uu) * r2) * q;
;                         w[2 * n + h] = cvt_pk2(o.x, o.y); }
;                 u32x4 wv; wv.x = w[0]; wv.y = w[1]; wv.z = w[2]; wv.w = w[3];
;                 *(u32x4*)rowp = wv; }
.Lalign_skip4:
	v_or_b32_e32 v97, 32, v153
	s_waitcnt lgkmcnt(0)
	v_mul_f32_e32 v96, 0xbfb8aa3b, v98
	v_pk_mul_f32 v[100:101], v[92:93], v[96:97] op_sel_hi:[1,0]
	v_pk_mul_f32 v[92:93], v[94:95], v[96:97] op_sel_hi:[1,0]
	v_exp_f32_e32 v100, v100
	v_exp_f32_e32 v92, v92
	v_exp_f32_e32 v93, v93
	v_exp_f32_e32 v101, v101
	v_mul_f32_e32 v98, v98, v98
	v_pk_mul_f32 v[90:91], v[94:95], v[90:91]
	v_pk_add_f32 v[92:93], v[92:93], 1.0 op_sel_hi:[1,0]
	v_pk_add_f32 v[100:101], v[100:101], 1.0 op_sel_hi:[1,0]
	v_rcp_f32_e32 v92, v92
	v_rcp_f32_e32 v93, v93
	v_rcp_f32_e32 v100, v100
	v_rcp_f32_e32 v101, v101
	v_pk_mul_f32 v[94:95], v[84:85], v[96:97] op_sel_hi:[1,0]
	v_pk_mul_f32 v[90:91], v[90:91], v[98:99] op_sel_hi:[1,0]
	v_exp_f32_e32 v94, v94
	v_exp_f32_e32 v95, v95
	v_pk_mul_f32 v[90:91], v[90:91], v[92:93]
	v_pk_mul_f32 v[92:93], v[86:87], v[96:97] op_sel_hi:[1,0]
	v_pk_mul_f32 v[88:89], v[88:89], v[98:99] op_sel_hi:[1,0]
	v_exp_f32_e32 v92, v92
	v_exp_f32_e32 v93, v93
	v_pk_mul_f32 v[88:89], v[88:89], v[100:101]
	v_pk_mul_f32 v[80:81], v[84:85], v[80:81]
	v_cvt_pk_bf16_f32 v88, v88, v89
	v_cvt_pk_bf16_f32 v89, v90, v91
	v_pk_add_f32 v[90:91], v[94:95], 1.0 op_sel_hi:[1,0]
	v_pk_add_f32 v[84:85], v[92:93], 1.0 op_sel_hi:[1,0]
	v_rcp_f32_e32 v90, v90
	v_rcp_f32_e32 v91, v91
	v_rcp_f32_e32 v84, v84
	v_rcp_f32_e32 v85, v85
	v_pk_mul_f32 v[80:81], v[80:81], v[98:99] op_sel_hi:[1,0]
	v_pk_mul_f32 v[82:83], v[86:87], v[82:83]
	v_pk_mul_f32 v[80:81], v[80:81], v[90:91]
	v_mad_i64_i32 v[102:103], s[20:21], v97, s61, v[144:145]
	v_cvt_pk_bf16_f32 v90, v80, v81
	v_pk_mul_f32 v[80:81], v[82:83], v[98:99] op_sel_hi:[1,0]
	v_pk_mul_f32 v[72:73], v[76:77], v[72:73]
	v_pk_mul_f32 v[80:81], v[80:81], v[84:85]
	v_pk_mul_f32 v[74:75], v[78:79], v[74:75]
	v_cvt_pk_bf16_f32 v91, v80, v81
	v_lshl_add_u64 v[80:81], v[102:103], 0, v[112:113]
	global_store_dwordx4 v[80:81], v[88:91], off
	v_or_b32_e32 v81, 48, v153
	v_mul_f32_e32 v80, 0xbfb8aa3b, v99
	v_pk_mul_f32 v[82:83], v[76:77], v[80:81] op_sel_hi:[1,0]
	v_pk_mul_f32 v[76:77], v[78:79], v[80:81] op_sel_hi:[1,0]
	v_exp_f32_e32 v82, v82
	v_exp_f32_e32 v83, v83
	v_exp_f32_e32 v76, v76
	v_exp_f32_e32 v77, v77
	v_pk_mul_f32 v[78:79], v[68:69], v[80:81] op_sel_hi:[1,0]
	v_pk_add_f32 v[82:83], v[82:83], 1.0 op_sel_hi:[1,0]
	v_exp_f32_e32 v78, v78
	v_pk_add_f32 v[76:77], v[76:77], 1.0 op_sel_hi:[1,0]
	v_rcp_f32_e32 v82, v82
	v_rcp_f32_e32 v83, v83
	v_rcp_f32_e32 v76, v76
	v_rcp_f32_e32 v77, v77
	v_exp_f32_e32 v79, v79
	v_mul_f32_e32 v86, v99, v99
	v_pk_mul_f32 v[72:73], v[72:73], v[86:87] op_sel_hi:[1,0]
	v_pk_mul_f32 v[74:75], v[74:75], v[86:87] op_sel_hi:[1,0]
	v_pk_mul_f32 v[72:73], v[72:73], v[82:83]
	v_pk_mul_f32 v[74:75], v[74:75], v[76:77]
	v_pk_mul_f32 v[76:77], v[70:71], v[80:81] op_sel_hi:[1,0]
	v_cvt_pk_bf16_f32 v72, v72, v73
	v_cvt_pk_bf16_f32 v73, v74, v75
	v_pk_add_f32 v[74:75], v[78:79], 1.0 op_sel_hi:[1,0]
	v_exp_f32_e32 v76, v76
	v_exp_f32_e32 v77, v77
	v_rcp_f32_e32 v74, v74
	v_rcp_f32_e32 v75, v75
	v_pk_mul_f32 v[64:65], v[68:69], v[64:65]
	v_pk_add_f32 v[68:69], v[76:77], 1.0 op_sel_hi:[1,0]
	v_pk_mul_f32 v[64:65], v[64:65], v[86:87] op_sel_hi:[1,0]
	v_pk_mul_f32 v[66:67], v[70:71], v[66:67]
	v_rcp_f32_e32 v68, v68
	v_rcp_f32_e32 v69, v69
	v_pk_mul_f32 v[64:65], v[64:65], v[74:75]
	v_mad_i64_i32 v[84:85], s[20:21], v81, s61, v[144:145]
	v_cvt_pk_bf16_f32 v74, v64, v65
	v_pk_mul_f32 v[64:65], v[66:67], v[86:87] op_sel_hi:[1,0]
	ds_read2_b32 v[66:67], v154 offset0:128 offset1:144
	v_pk_mul_f32 v[64:65], v[64:65], v[68:69]
	v_pk_mul_f32 v[56:57], v[60:61], v[56:57]
	v_cvt_pk_bf16_f32 v75, v64, v65
	v_lshl_add_u64 v[64:65], v[84:85], 0, v[112:113]
	global_store_dwordx4 v[64:65], v[72:75], off
	v_add_u32_e32 v65, 0x80, v153
	s_waitcnt lgkmcnt(0)
	v_mul_f32_e32 v64, 0xbfb8aa3b, v66
	v_pk_mul_f32 v[68:69], v[60:61], v[64:65] op_sel_hi:[1,0]
	v_pk_mul_f32 v[60:61], v[62:63], v[64:65] op_sel_hi:[1,0]
	v_exp_f32_e32 v68, v68
	v_exp_f32_e32 v60, v60
	v_exp_f32_e32 v61, v61
	v_exp_f32_e32 v69, v69
	v_mul_f32_e32 v66, v66, v66
	v_pk_mul_f32 v[58:59], v[62:63], v[58:59]
	v_pk_add_f32 v[60:61], v[60:61], 1.0 op_sel_hi:[1,0]
	v_pk_add_f32 v[68:69], v[68:69], 1.0 op_sel_hi:[1,0]
	v_rcp_f32_e32 v60, v60
	v_rcp_f32_e32 v61, v61
	v_rcp_f32_e32 v68, v68
	v_rcp_f32_e32 v69, v69
	v_pk_mul_f32 v[62:63], v[52:53], v[64:65] op_sel_hi:[1,0]
	v_pk_mul_f32 v[58:59], v[58:59], v[66:67] op_sel_hi:[1,0]
	v_exp_f32_e32 v62, v62
	v_exp_f32_e32 v63, v63
	v_pk_mul_f32 v[58:59], v[58:59], v[60:61]
	v_pk_mul_f32 v[60:61], v[54:55], v[64:65] op_sel_hi:[1,0]
	v_pk_mul_f32 v[56:57], v[56:57], v[66:67] op_sel_hi:[1,0]
	v_exp_f32_e32 v60, v60
	v_exp_f32_e32 v61, v61
	v_pk_mul_f32 v[56:57], v[56:57], v[68:69]
	v_pk_mul_f32 v[48:49], v[52:53], v[48:49]
	v_cvt_pk_bf16_f32 v56, v56, v57
	v_cvt_pk_bf16_f32 v57, v58, v59
	v_pk_add_f32 v[58:59], v[62:63], 1.0 op_sel_hi:[1,0]
	v_pk_add_f32 v[52:53], v[60:61], 1.0 op_sel_hi:[1,0]
	v_rcp_f32_e32 v58, v58
	v_rcp_f32_e32 v59, v59
	v_rcp_f32_e32 v52, v52
	v_rcp_f32_e32 v53, v53
	v_pk_mul_f32 v[48:49], v[48:49], v[66:67] op_sel_hi:[1,0]
	v_pk_mul_f32 v[50:51], v[54:55], v[50:51]
	v_pk_mul_f32 v[48:49], v[48:49], v[58:59]
	v_mad_i64_i32 v[70:71], s[20:21], v65, s61, v[144:145]
	v_cvt_pk_bf16_f32 v58, v48, v49
	v_pk_mul_f32 v[48:49], v[50:51], v[66:67] op_sel_hi:[1,0]
	v_pk_mul_f32 v[40:41], v[44:45], v[40:41]
	v_pk_mul_f32 v[48:49], v[48:49], v[52:53]
	v_pk_mul_f32 v[42:43], v[46:47], v[42:43]
	v_cvt_pk_bf16_f32 v59, v48, v49
	v_lshl_add_u64 v[48:49], v[70:71], 0, v[112:113]
; #define PG8_BAR __builtin_amdgcn_s_barrier()
; __device__ __forceinline__ unsigned cvt_pk2(float lo, float hi) { f32x2c v = {lo, hi}; bf16x2c q = __builtin_convertvector(v, bf16x2c); return __builtin_bit_cast(unsigned, q); }
; template <class Epi, class Sched, bool ALIGN_EPI = false, bool SP2 = false>
; __device__ __forceinline__ void gemm_phase(PG8_LAS unsigned char* lds, const Gemm g, const Sched& S, const Epi& E) {
;     ...
;         if constexpr (ALIGN_EPI) { if (wr == 1) PG8_BAR; }
;     __device__ __forceinline__ void operator()(const f32x4 (&acc)[2][2][4][2], const pg8::Unit& u, int wr, int wc, int fr, int fq) const {
;     ...
;             for (int m = 0; m < 4; ++m) { bf16_t* rowp = O + (size_t)(row0 + ai * 128 + m * 16) * FF + col0; const float r = rt[ai * 128 + m * 16];
;                 const float rl = -r * LOG2E, r2 = r * r; unsigned w[4];
; #pragma unroll
;                 for (int n = 0; n < 2; ++n)
; #pragma unroll
;                     for (int h = 0; h < 2; ++h) { const f32x2v g = {acc[ai][0][m][n][2 * h], acc[ai][0][m][n][2 * h + 1]}, uu = {acc[ai][1][m][n][2 * h], acc[ai][1][m][n][2 * h + 1]};
;                         const f32x2v t = g * rl; f32x2v d = {__builtin_amdgcn_exp2f(t.x), __builtin_amdgcn_exp2f(t.y)}; d = d + 1.0f;
;                         const f32x2v q = {__builtin_amdgcn_rcpf(d.x), __builtin_amdgcn_rcpf(d.y)}; const f32x2v o = ((g * uu) * r2) * q;
;                         w[2 * n + h] = cvt_pk2(o.x, o.y); }
;                 u32x4 wv; wv.x = w[0]; wv.y = w[1]; wv.z = w[2]; wv.w = w[3];
;                 *(u32x4*)rowp = wv; }
	global_store_dwordx4 v[48:49], v[56:59], off
	v_add_u32_e32 v49, 0x90, v153
	v_mul_f32_e32 v48, 0xbfb8aa3b, v67
	v_pk_mul_f32 v[50:51], v[44:45], v[48:49] op_sel_hi:[1,0]
	v_pk_mul_f32 v[44:45], v[46:47], v[48:49] op_sel_hi:[1,0]
	v_exp_f32_e32 v50, v50
	v_exp_f32_e32 v51, v51
	v_exp_f32_e32 v44, v44
	v_exp_f32_e32 v45, v45
	v_pk_mul_f32 v[46:47], v[36:37], v[48:49] op_sel_hi:[1,0]
	v_pk_add_f32 v[50:51], v[50:51], 1.0 op_sel_hi:[1,0]
	v_exp_f32_e32 v46, v46
	v_pk_add_f32 v[44:45], v[44:45], 1.0 op_sel_hi:[1,0]
	v_rcp_f32_e32 v50, v50
	v_rcp_f32_e32 v51, v51
	v_rcp_f32_e32 v44, v44
	v_rcp_f32_e32 v45, v45
	v_exp_f32_e32 v47, v47
	v_mul_f32_e32 v54, v67, v67
	v_pk_mul_f32 v[40:41], v[40:41], v[54:55] op_sel_hi:[1,0]
	v_pk_mul_f32 v[42:43], v[42:43], v[54:55] op_sel_hi:[1,0]
	v_pk_mul_f32 v[40:41], v[40:41], v[50:51]
	v_pk_mul_f32 v[42:43], v[42:43], v[44:45]
	v_pk_mul_f32 v[44:45], v[38:39], v[48:49] op_sel_hi:[1,0]
	v_cvt_pk_bf16_f32 v40, v40, v41
	v_cvt_pk_bf16_f32 v41, v42, v43
	v_pk_add_f32 v[42:43], v[46:47], 1.0 op_sel_hi:[1,0]
	v_exp_f32_e32 v44, v44
	v_exp_f32_e32 v45, v45
	v_rcp_f32_e32 v42, v42
	v_rcp_f32_e32 v43, v43
	v_pk_mul_f32 v[32:33], v[36:37], v[32:33]
	v_pk_add_f32 v[36:37], v[44:45], 1.0 op_sel_hi:[1,0]
	v_pk_mul_f32 v[32:33], v[32:33], v[54:55] op_sel_hi:[1,0]
	v_pk_mul_f32 v[34:35], v[38:39], v[34:35]
	v_rcp_f32_e32 v36, v36
	v_rcp_f32_e32 v37, v37
	v_pk_mul_f32 v[32:33], v[32:33], v[42:43]
	v_mad_i64_i32 v[52:53], s[20:21], v49, s61, v[144:145]
	v_cvt_pk_bf16_f32 v42, v32, v33
	v_pk_mul_f32 v[32:33], v[34:35], v[54:55] op_sel_hi:[1,0]
	ds_read2_b32 v[34:35], v154 offset0:160 offset1:176
	v_pk_mul_f32 v[32:33], v[32:33], v[36:37]
	v_pk_mul_f32 v[24:25], v[28:29], v[24:25]
	v_cvt_pk_bf16_f32 v43, v32, v33
	v_lshl_add_u64 v[32:33], v[52:53], 0, v[112:113]
	global_store_dwordx4 v[32:33], v[40:43], off
	v_add_u32_e32 v33, 0xa0, v153
	s_waitcnt lgkmcnt(0)
	v_mul_f32_e32 v32, 0xbfb8aa3b, v34
	v_pk_mul_f32 v[36:37], v[28:29], v[32:33] op_sel_hi:[1,0]
	v_pk_mul_f32 v[28:29], v[30:31], v[32:33] op_sel_hi:[1,0]
	v_exp_f32_e32 v36, v36
	v_exp_f32_e32 v28, v28
	v_exp_f32_e32 v29, v29
	v_exp_f32_e32 v37, v37
	v_mul_f32_e32 v34, v34, v34
	v_pk_mul_f32 v[26:27], v[30:31], v[26:27]
	v_pk_add_f32 v[28:29], v[28:29], 1.0 op_sel_hi:[1,0]
	v_pk_add_f32 v[36:37], v[36:37], 1.0 op_sel_hi:[1,0]
	v_rcp_f32_e32 v28, v28
	v_rcp_f32_e32 v29, v29
	v_rcp_f32_e32 v36, v36
	v_rcp_f32_e32 v37, v37
	v_pk_mul_f32 v[30:31], v[20:21], v[32:33] op_sel_hi:[1,0]
	v_pk_mul_f32 v[26:27], v[26:27], v[34:35] op_sel_hi:[1,0]
	v_exp_f32_e32 v30, v30
	v_exp_f32_e32 v31, v31
	v_pk_mul_f32 v[26:27], v[26:27], v[28:29]
	v_pk_mul_f32 v[28:29], v[22:23], v[32:33] op_sel_hi:[1,0]
	v_pk_mul_f32 v[24:25], v[24:25], v[34:35] op_sel_hi:[1,0]
	v_exp_f32_e32 v28, v28
	v_exp_f32_e32 v29, v29
	v_pk_mul_f32 v[24:25], v[24:25], v[36:37]
	v_pk_mul_f32 v[16:17], v[20:21], v[16:17]
	v_cvt_pk_bf16_f32 v24, v24, v25
	v_cvt_pk_bf16_f32 v25, v26, v27
	v_pk_add_f32 v[26:27], v[30:31], 1.0 op_sel_hi:[1,0]
	v_pk_add_f32 v[20:21], v[28:29], 1.0 op_sel_hi:[1,0]
	v_rcp_f32_e32 v26, v26
	v_rcp_f32_e32 v27, v27
	v_rcp_f32_e32 v20, v20
	v_rcp_f32_e32 v21, v21
	v_pk_mul_f32 v[16:17], v[16:17], v[34:35] op_sel_hi:[1,0]
	v_pk_mul_f32 v[18:19], v[22:23], v[18:19]
	v_pk_mul_f32 v[16:17], v[16:17], v[26:27]
	v_mad_i64_i32 v[38:39], s[20:21], v33, s61, v[144:145]
	v_cvt_pk_bf16_f32 v26, v16, v17
	v_pk_mul_f32 v[16:17], v[18:19], v[34:35] op_sel_hi:[1,0]
	v_pk_mul_f32 v[8:9], v[12:13], v[8:9]
	v_pk_mul_f32 v[16:17], v[16:17], v[20:21]
	v_mul_f32_e32 v22, v35, v35
	v_cvt_pk_bf16_f32 v27, v16, v17
	v_lshl_add_u64 v[16:17], v[38:39], 0, v[112:113]
	global_store_dwordx4 v[16:17], v[24:27], off
	v_add_u32_e32 v17, 0xb0, v153
	v_mul_f32_e32 v16, 0xbfb8aa3b, v35
	v_pk_mul_f32 v[18:19], v[12:13], v[16:17] op_sel_hi:[1,0]
	v_pk_mul_f32 v[12:13], v[14:15], v[16:17] op_sel_hi:[1,0]
	v_exp_f32_e32 v18, v18
	v_exp_f32_e32 v12, v12
	v_exp_f32_e32 v13, v13
	v_exp_f32_e32 v19, v19
	v_pk_mul_f32 v[10:11], v[14:15], v[10:11]
	v_pk_mul_f32 v[14:15], v[4:5], v[16:17] op_sel_hi:[1,0]
	v_pk_add_f32 v[12:13], v[12:13], 1.0 op_sel_hi:[1,0]
	v_pk_add_f32 v[18:19], v[18:19], 1.0 op_sel_hi:[1,0]
	v_rcp_f32_e32 v12, v12
	v_rcp_f32_e32 v13, v13
	v_rcp_f32_e32 v18, v18
	v_rcp_f32_e32 v19, v19
	v_exp_f32_e32 v14, v14
	v_exp_f32_e32 v15, v15
	v_pk_mul_f32 v[10:11], v[10:11], v[22:23] op_sel_hi:[1,0]
	v_pk_mul_f32 v[8:9], v[8:9], v[22:23] op_sel_hi:[1,0]
	v_pk_mul_f32 v[10:11], v[10:11], v[12:13]
	v_pk_mul_f32 v[12:13], v[6:7], v[16:17] op_sel_hi:[1,0]
	v_pk_mul_f32 v[8:9], v[8:9], v[18:19]
	v_exp_f32_e32 v12, v12
	v_exp_f32_e32 v13, v13
	v_cvt_pk_bf16_f32 v8, v8, v9
	v_cvt_pk_bf16_f32 v9, v10, v11
	v_pk_add_f32 v[10:11], v[14:15], 1.0 op_sel_hi:[1,0]
	v_pk_mul_f32 v[0:1], v[4:5], v[0:1]
	v_rcp_f32_e32 v10, v10
	v_rcp_f32_e32 v11, v11
	v_pk_add_f32 v[4:5], v[12:13], 1.0 op_sel_hi:[1,0]
	v_pk_mul_f32 v[0:1], v[0:1], v[22:23] op_sel_hi:[1,0]
	v_rcp_f32_e32 v4, v4
	v_rcp_f32_e32 v5, v5
	v_pk_mul_f32 v[2:3], v[6:7], v[2:3]
	v_pk_mul_f32 v[0:1], v[0:1], v[10:11]
	v_mad_i64_i32 v[20:21], s[20:21], v17, s61, v[144:145]
	v_cvt_pk_bf16_f32 v10, v0, v1
	v_pk_mul_f32 v[0:1], v[2:3], v[22:23] op_sel_hi:[1,0]
	s_andn2_b64 vcc, exec, s[4:5]
	v_pk_mul_f32 v[0:1], v[0:1], v[4:5]
	s_mov_b64 s[4:5], -1
	v_cvt_pk_bf16_f32 v11, v0, v1
	v_lshl_add_u64 v[0:1], v[20:21], 0, v[112:113]
	global_store_dwordx4 v[0:1], v[8:11], off
	s_cbranch_vccnz .LBB0_1736
	s_andn2_b64 vcc, exec, s[0:1]
	s_cbranch_vccnz .LBB0_1735
	s_barrier
	s_branch .LBB0_1735
